# v16 + uq/ukv pre-hook (sum-of-squares loads + 1/rms) moved from the K-loop header (run by each half in turn) to the half-aligned epilogue head (run once, concurrently)
# speedup vs baseline: 1.0039x; 1.0014x over previous
.LBB0_438:
	s_add_u32 s0, s8, s10
	s_addc_u32 s1, s9, s11
	s_add_u32 s0, s0, 0x100
	s_addc_u32 s1, s1, 0
	s_add_u32 s59, s54, s10
	s_addc_u32 s60, s55, s11
	s_add_i32 s61, 0, 0x10000
	s_cmpk_eq_i32 s10, 0x700
	s_cselect_b32 s13, s3, s1
	s_cselect_b32 s12, s21, s0
	s_cselect_b32 s1, s47, s60
	s_cselect_b32 s0, s53, s59
	s_add_i32 s59, 0, 0x14000
	v_add_u32_e32 v168, s61, v188
	v_add_u32_e32 v176, s59, v188
	ds_read_b128 v[132:135], v168
	ds_read_b128 v[136:139], v168 offset:1024
	ds_read_b128 v[140:143], v168 offset:2048
	ds_read_b128 v[168:171], v168 offset:3072
	ds_read_b128 v[172:175], v176
	ds_read_b128 v[194:197], v176 offset:1024
	ds_read_b128 v[198:201], v176 offset:2048
	ds_read_b128 v[202:205], v176 offset:3072
	v_lshl_add_u64 v[176:177], v[164:165], 0, s[10:11]
	s_add_i32 m0, s18, 0xc000
	ds_read_b128 v[214:217], v190
	ds_read_b128 v[218:221], v190 offset:1024
	ds_read_b128 v[222:225], v190 offset:2048
	ds_read_b128 v[226:229], v190 offset:3072
	ds_read_b128 v[230:233], v190 offset:4096
	ds_read_b128 v[234:237], v190 offset:5120
	ds_read_b128 v[238:241], v190 offset:6144
	ds_read_b128 v[242:245], v190 offset:7168
	global_load_lds_dwordx4 v[176:177], off
	v_lshl_add_u64 v[176:177], v[166:167], 0, s[10:11]
	s_add_i32 m0, s18, 0xe000
	s_nop 0
	global_load_lds_dwordx4 v[176:177], off
	s_waitcnt vmcnt(8)
	s_waitcnt lgkmcnt(0)
	s_barrier
	s_setprio 1
	s_waitcnt lgkmcnt(0)
	v_mfma_f32_16x16x32_bf16 v[128:131], v[132:135], v[214:217], v[128:131]
	v_mfma_f32_16x16x32_bf16 v[124:127], v[140:143], v[214:217], v[124:127]
	v_mfma_f32_16x16x32_bf16 v[112:115], v[132:135], v[222:225], v[112:115]
	v_mfma_f32_16x16x32_bf16 v[108:111], v[140:143], v[222:225], v[108:111]
	v_mfma_f32_16x16x32_bf16 v[96:99], v[132:135], v[230:233], v[96:99]
	v_mfma_f32_16x16x32_bf16 v[92:95], v[140:143], v[230:233], v[92:95]
	v_mfma_f32_16x16x32_bf16 v[80:83], v[132:135], v[238:241], v[80:83]
	v_mfma_f32_16x16x32_bf16 v[76:79], v[140:143], v[238:241], v[76:79]
	v_mfma_f32_16x16x32_bf16 v[128:131], v[136:139], v[218:221], v[128:131]
	v_mfma_f32_16x16x32_bf16 v[124:127], v[168:171], v[218:221], v[124:127]
	v_mfma_f32_16x16x32_bf16 v[112:115], v[136:139], v[226:229], v[112:115]
	v_mfma_f32_16x16x32_bf16 v[108:111], v[168:171], v[226:229], v[108:111]
	v_mfma_f32_16x16x32_bf16 v[96:99], v[136:139], v[234:237], v[96:99]
	v_mfma_f32_16x16x32_bf16 v[92:95], v[168:171], v[234:237], v[92:95]
	v_mfma_f32_16x16x32_bf16 v[80:83], v[136:139], v[242:245], v[80:83]
	v_mfma_f32_16x16x32_bf16 v[76:79], v[168:171], v[242:245], v[76:79]
	s_setprio 0
	s_setprio 1
	v_mfma_f32_16x16x32_bf16 v[120:123], v[172:175], v[214:217], v[120:123]
	v_mfma_f32_16x16x32_bf16 v[116:119], v[198:201], v[214:217], v[116:119]
	v_mfma_f32_16x16x32_bf16 v[104:107], v[172:175], v[222:225], v[104:107]
	v_mfma_f32_16x16x32_bf16 v[100:103], v[198:201], v[222:225], v[100:103]
	v_mfma_f32_16x16x32_bf16 v[88:91], v[172:175], v[230:233], v[88:91]
	v_mfma_f32_16x16x32_bf16 v[84:87], v[198:201], v[230:233], v[84:87]
	v_mfma_f32_16x16x32_bf16 v[72:75], v[172:175], v[238:241], v[72:75]
	v_mfma_f32_16x16x32_bf16 v[68:71], v[198:201], v[238:241], v[68:71]
	v_mfma_f32_16x16x32_bf16 v[120:123], v[194:197], v[218:221], v[120:123]
	v_mfma_f32_16x16x32_bf16 v[116:119], v[202:205], v[218:221], v[116:119]
	v_mfma_f32_16x16x32_bf16 v[104:107], v[194:197], v[226:229], v[104:107]
	v_mfma_f32_16x16x32_bf16 v[100:103], v[202:205], v[226:229], v[100:103]
	v_mfma_f32_16x16x32_bf16 v[88:91], v[194:197], v[234:237], v[88:91]
	v_mfma_f32_16x16x32_bf16 v[84:87], v[202:205], v[234:237], v[84:87]
	v_mfma_f32_16x16x32_bf16 v[72:75], v[194:197], v[242:245], v[72:75]
	v_mfma_f32_16x16x32_bf16 v[68:71], v[202:205], v[242:245], v[68:71]
	s_setprio 0
	s_barrier
	s_add_i32 s60, s61, s15
	v_lshl_add_u64 v[176:177], s[0:1], 0, v[148:149]
	s_mov_b32 m0, s60
	ds_read_b128 v[214:217], v190 offset:16384
	ds_read_b128 v[218:221], v190 offset:17408
	ds_read_b128 v[222:225], v190 offset:18432
	ds_read_b128 v[226:229], v190 offset:19456
	ds_read_b128 v[230:233], v190 offset:20480
	ds_read_b128 v[234:237], v190 offset:21504
	ds_read_b128 v[238:241], v190 offset:22528
	ds_read_b128 v[242:245], v190 offset:23552
	global_load_lds_dwordx4 v[176:177], off
	s_add_i32 m0, s60, 0x2000
	s_add_u32 s60, s0, 0x40000
	v_lshl_add_u64 v[180:181], s[0:1], 0, v[144:145]
	s_addc_u32 s61, s1, 0
	s_add_i32 s59, s59, s15
	global_load_lds_dwordx4 v[180:181], off
	v_lshl_add_u64 v[182:183], s[60:61], 0, v[148:149]
	s_mov_b32 m0, s59
	v_lshl_add_u64 v[184:185], s[12:13], 0, v[146:147]
	global_load_lds_dwordx4 v[182:183], off
	v_lshl_add_u64 v[182:183], s[60:61], 0, v[144:145]
	s_add_i32 m0, s59, 0x2000
	s_nop 0
	global_load_lds_dwordx4 v[182:183], off
	v_lshl_add_u64 v[182:183], s[12:13], 0, v[150:151]
	s_mov_b32 m0, s18
	s_nop 0
	global_load_lds_dwordx4 v[182:183], off
	s_mov_b32 m0, s19
	s_nop 0
	global_load_lds_dwordx4 v[184:185], off
	s_waitcnt vmcnt(8)
	s_waitcnt lgkmcnt(0)
	s_barrier
	s_setprio 1
	s_waitcnt lgkmcnt(0)
	v_mfma_f32_16x16x32_bf16 v[64:67], v[132:135], v[214:217], v[64:67]
	v_mfma_f32_16x16x32_bf16 v[60:63], v[140:143], v[214:217], v[60:63]
	v_mfma_f32_16x16x32_bf16 v[48:51], v[132:135], v[222:225], v[48:51]
	v_mfma_f32_16x16x32_bf16 v[44:47], v[140:143], v[222:225], v[44:47]
	v_mfma_f32_16x16x32_bf16 v[32:35], v[132:135], v[230:233], v[32:35]
	v_mfma_f32_16x16x32_bf16 v[28:31], v[140:143], v[230:233], v[28:31]
	v_mfma_f32_16x16x32_bf16 v[16:19], v[132:135], v[238:241], v[16:19]
	v_mfma_f32_16x16x32_bf16 v[12:15], v[140:143], v[238:241], v[12:15]
	v_mfma_f32_16x16x32_bf16 v[64:67], v[136:139], v[218:221], v[64:67]
	v_mfma_f32_16x16x32_bf16 v[60:63], v[168:171], v[218:221], v[60:63]
	v_mfma_f32_16x16x32_bf16 v[48:51], v[136:139], v[226:229], v[48:51]
	v_mfma_f32_16x16x32_bf16 v[44:47], v[168:171], v[226:229], v[44:47]
	v_mfma_f32_16x16x32_bf16 v[32:35], v[136:139], v[234:237], v[32:35]
	v_mfma_f32_16x16x32_bf16 v[28:31], v[168:171], v[234:237], v[28:31]
	v_mfma_f32_16x16x32_bf16 v[16:19], v[136:139], v[242:245], v[16:19]
	v_mfma_f32_16x16x32_bf16 v[12:15], v[168:171], v[242:245], v[12:15]
	s_setprio 0
	s_setprio 1
	v_mfma_f32_16x16x32_bf16 v[56:59], v[172:175], v[214:217], v[56:59]
	v_mfma_f32_16x16x32_bf16 v[52:55], v[198:201], v[214:217], v[52:55]
	v_mfma_f32_16x16x32_bf16 v[40:43], v[172:175], v[222:225], v[40:43]
	v_mfma_f32_16x16x32_bf16 v[36:39], v[198:201], v[222:225], v[36:39]
	v_mfma_f32_16x16x32_bf16 v[24:27], v[172:175], v[230:233], v[24:27]
	v_mfma_f32_16x16x32_bf16 v[20:23], v[198:201], v[230:233], v[20:23]
	v_mfma_f32_16x16x32_bf16 v[8:11], v[172:175], v[238:241], v[8:11]
	v_mfma_f32_16x16x32_bf16 v[4:7], v[198:201], v[238:241], v[4:7]
	v_mfma_f32_16x16x32_bf16 v[56:59], v[194:197], v[218:221], v[56:59]
	v_mfma_f32_16x16x32_bf16 v[52:55], v[202:205], v[218:221], v[52:55]
	v_mfma_f32_16x16x32_bf16 v[40:43], v[194:197], v[226:229], v[40:43]
	v_mfma_f32_16x16x32_bf16 v[36:39], v[202:205], v[226:229], v[36:39]
	v_mfma_f32_16x16x32_bf16 v[24:27], v[194:197], v[234:237], v[24:27]
	v_mfma_f32_16x16x32_bf16 v[20:23], v[202:205], v[234:237], v[20:23]
	v_mfma_f32_16x16x32_bf16 v[8:11], v[194:197], v[242:245], v[8:11]
	v_mfma_f32_16x16x32_bf16 v[4:7], v[202:205], v[242:245], v[4:7]
	s_setprio 0
	s_barrier
	s_add_i32 s59, 0, 0x18000
	s_add_i32 s60, 0, 0x1c000
	v_add_u32_e32 v168, s59, v188
	v_add_u32_e32 v193, s60, v188
	ds_read_b128 v[132:135], v168
	ds_read_b128 v[136:139], v168 offset:1024
	ds_read_b128 v[140:143], v168 offset:2048
	ds_read_b128 v[168:171], v168 offset:3072
	ds_read_b128 v[172:175], v193
	ds_read_b128 v[194:197], v193 offset:1024
	ds_read_b128 v[198:201], v193 offset:2048
	ds_read_b128 v[202:205], v193 offset:3072
	s_add_u32 s12, s12, 0x40000
	s_addc_u32 s13, s13, 0
	s_mov_b32 m0, s23
	v_lshl_add_u64 v[206:207], s[12:13], 0, v[150:151]
	ds_read_b128 v[214:217], v190 offset:32768
	ds_read_b128 v[218:221], v190 offset:33792
	ds_read_b128 v[222:225], v190 offset:34816
	ds_read_b128 v[226:229], v190 offset:35840
	ds_read_b128 v[230:233], v190 offset:36864
	ds_read_b128 v[234:237], v190 offset:37888
	ds_read_b128 v[238:241], v190 offset:38912
	ds_read_b128 v[242:245], v190 offset:39936
	global_load_lds_dwordx4 v[206:207], off
	v_lshl_add_u64 v[206:207], s[12:13], 0, v[146:147]
	s_mov_b32 m0, s24
	s_nop 0
	global_load_lds_dwordx4 v[206:207], off
	s_waitcnt vmcnt(8)
	s_waitcnt lgkmcnt(0)
	s_barrier
	s_setprio 1
	s_waitcnt lgkmcnt(0)
	v_mfma_f32_16x16x32_bf16 v[128:131], v[132:135], v[214:217], v[128:131]
	v_mfma_f32_16x16x32_bf16 v[124:127], v[140:143], v[214:217], v[124:127]
	v_mfma_f32_16x16x32_bf16 v[112:115], v[132:135], v[222:225], v[112:115]
	v_mfma_f32_16x16x32_bf16 v[108:111], v[140:143], v[222:225], v[108:111]
	v_mfma_f32_16x16x32_bf16 v[96:99], v[132:135], v[230:233], v[96:99]
	v_mfma_f32_16x16x32_bf16 v[92:95], v[140:143], v[230:233], v[92:95]
	v_mfma_f32_16x16x32_bf16 v[80:83], v[132:135], v[238:241], v[80:83]
	v_mfma_f32_16x16x32_bf16 v[76:79], v[140:143], v[238:241], v[76:79]
	v_mfma_f32_16x16x32_bf16 v[128:131], v[136:139], v[218:221], v[128:131]
	v_mfma_f32_16x16x32_bf16 v[124:127], v[168:171], v[218:221], v[124:127]
	v_mfma_f32_16x16x32_bf16 v[112:115], v[136:139], v[226:229], v[112:115]
	v_mfma_f32_16x16x32_bf16 v[108:111], v[168:171], v[226:229], v[108:111]
	v_mfma_f32_16x16x32_bf16 v[96:99], v[136:139], v[234:237], v[96:99]
	v_mfma_f32_16x16x32_bf16 v[92:95], v[168:171], v[234:237], v[92:95]
	v_mfma_f32_16x16x32_bf16 v[80:83], v[136:139], v[242:245], v[80:83]
	v_mfma_f32_16x16x32_bf16 v[76:79], v[168:171], v[242:245], v[76:79]
	s_setprio 0
	s_setprio 1
	v_mfma_f32_16x16x32_bf16 v[120:123], v[172:175], v[214:217], v[120:123]
	v_mfma_f32_16x16x32_bf16 v[116:119], v[198:201], v[214:217], v[116:119]
	v_mfma_f32_16x16x32_bf16 v[104:107], v[172:175], v[222:225], v[104:107]
	v_mfma_f32_16x16x32_bf16 v[100:103], v[198:201], v[222:225], v[100:103]
	v_mfma_f32_16x16x32_bf16 v[88:91], v[172:175], v[230:233], v[88:91]
	v_mfma_f32_16x16x32_bf16 v[84:87], v[198:201], v[230:233], v[84:87]
	v_mfma_f32_16x16x32_bf16 v[72:75], v[172:175], v[238:241], v[72:75]
	v_mfma_f32_16x16x32_bf16 v[68:71], v[198:201], v[238:241], v[68:71]
	v_mfma_f32_16x16x32_bf16 v[120:123], v[194:197], v[218:221], v[120:123]
	v_mfma_f32_16x16x32_bf16 v[116:119], v[202:205], v[218:221], v[116:119]
	v_mfma_f32_16x16x32_bf16 v[104:107], v[194:197], v[226:229], v[104:107]
	v_mfma_f32_16x16x32_bf16 v[100:103], v[202:205], v[226:229], v[100:103]
	v_mfma_f32_16x16x32_bf16 v[88:91], v[194:197], v[234:237], v[88:91]
	v_mfma_f32_16x16x32_bf16 v[84:87], v[202:205], v[234:237], v[84:87]
	v_mfma_f32_16x16x32_bf16 v[72:75], v[194:197], v[242:245], v[72:75]
	v_mfma_f32_16x16x32_bf16 v[68:71], v[202:205], v[242:245], v[68:71]
	s_setprio 0
	s_barrier
	s_add_i32 s12, s59, s15
	v_lshl_add_u64 v[176:177], v[176:177], 0, s[34:35]
	s_mov_b32 m0, s12
	ds_read_b128 v[214:217], v190 offset:49152
	ds_read_b128 v[218:221], v190 offset:50176
	ds_read_b128 v[222:225], v190 offset:51200
	ds_read_b128 v[226:229], v190 offset:52224
	ds_read_b128 v[230:233], v190 offset:53248
	ds_read_b128 v[234:237], v190 offset:54272
	ds_read_b128 v[238:241], v190 offset:55296
	ds_read_b128 v[242:245], v190 offset:56320
	global_load_lds_dwordx4 v[176:177], off
	s_add_i32 m0, s12, 0x2000
	s_add_u32 s0, s0, 0x40080
	v_lshl_add_u64 v[176:177], v[180:181], 0, s[34:35]
	s_addc_u32 s1, s1, 0
	s_add_i32 s12, s60, s15
	global_load_lds_dwordx4 v[176:177], off
	v_lshl_add_u64 v[176:177], s[0:1], 0, v[148:149]
	s_mov_b32 m0, s12
	s_nop 0
	global_load_lds_dwordx4 v[176:177], off
	v_lshl_add_u64 v[176:177], s[0:1], 0, v[144:145]
	s_add_i32 m0, s12, 0x2000
	s_nop 0
	global_load_lds_dwordx4 v[176:177], off
	v_lshl_add_u64 v[176:177], v[182:183], 0, s[34:35]
	s_mov_b32 m0, s25
	s_nop 0
	global_load_lds_dwordx4 v[176:177], off
	v_lshl_add_u64 v[176:177], v[184:185], 0, s[34:35]
	s_mov_b32 m0, s30
	s_nop 0
	global_load_lds_dwordx4 v[176:177], off
	s_waitcnt vmcnt(8)
	s_waitcnt lgkmcnt(0)
	s_barrier
	s_setprio 1
	s_waitcnt lgkmcnt(0)
	v_mfma_f32_16x16x32_bf16 v[64:67], v[132:135], v[214:217], v[64:67]
	v_mfma_f32_16x16x32_bf16 v[60:63], v[140:143], v[214:217], v[60:63]
	v_mfma_f32_16x16x32_bf16 v[48:51], v[132:135], v[222:225], v[48:51]
	v_mfma_f32_16x16x32_bf16 v[44:47], v[140:143], v[222:225], v[44:47]
	v_mfma_f32_16x16x32_bf16 v[32:35], v[132:135], v[230:233], v[32:35]
	v_mfma_f32_16x16x32_bf16 v[28:31], v[140:143], v[230:233], v[28:31]
	v_mfma_f32_16x16x32_bf16 v[16:19], v[132:135], v[238:241], v[16:19]
	v_mfma_f32_16x16x32_bf16 v[12:15], v[140:143], v[238:241], v[12:15]
	v_mfma_f32_16x16x32_bf16 v[64:67], v[136:139], v[218:221], v[64:67]
	v_mfma_f32_16x16x32_bf16 v[60:63], v[168:171], v[218:221], v[60:63]
	v_mfma_f32_16x16x32_bf16 v[48:51], v[136:139], v[226:229], v[48:51]
	v_mfma_f32_16x16x32_bf16 v[44:47], v[168:171], v[226:229], v[44:47]
	v_mfma_f32_16x16x32_bf16 v[32:35], v[136:139], v[234:237], v[32:35]
	v_mfma_f32_16x16x32_bf16 v[28:31], v[168:171], v[234:237], v[28:31]
	v_mfma_f32_16x16x32_bf16 v[16:19], v[136:139], v[242:245], v[16:19]
	v_mfma_f32_16x16x32_bf16 v[12:15], v[168:171], v[242:245], v[12:15]
	s_setprio 0
	s_setprio 1
	v_mfma_f32_16x16x32_bf16 v[56:59], v[172:175], v[214:217], v[56:59]
	v_mfma_f32_16x16x32_bf16 v[52:55], v[198:201], v[214:217], v[52:55]
	v_mfma_f32_16x16x32_bf16 v[40:43], v[172:175], v[222:225], v[40:43]
	v_mfma_f32_16x16x32_bf16 v[36:39], v[198:201], v[222:225], v[36:39]
	v_mfma_f32_16x16x32_bf16 v[24:27], v[172:175], v[230:233], v[24:27]
	v_mfma_f32_16x16x32_bf16 v[20:23], v[198:201], v[230:233], v[20:23]
	v_mfma_f32_16x16x32_bf16 v[8:11], v[172:175], v[238:241], v[8:11]
	v_mfma_f32_16x16x32_bf16 v[4:7], v[198:201], v[238:241], v[4:7]
	v_mfma_f32_16x16x32_bf16 v[56:59], v[194:197], v[218:221], v[56:59]
	v_mfma_f32_16x16x32_bf16 v[52:55], v[202:205], v[218:221], v[52:55]
	v_mfma_f32_16x16x32_bf16 v[40:43], v[194:197], v[226:229], v[40:43]
	v_mfma_f32_16x16x32_bf16 v[36:39], v[202:205], v[226:229], v[36:39]
	v_mfma_f32_16x16x32_bf16 v[24:27], v[194:197], v[234:237], v[24:27]
	v_mfma_f32_16x16x32_bf16 v[20:23], v[202:205], v[234:237], v[20:23]
	v_mfma_f32_16x16x32_bf16 v[8:11], v[194:197], v[242:245], v[8:11]
	v_mfma_f32_16x16x32_bf16 v[4:7], v[202:205], v[242:245], v[4:7]
	s_setprio 0
	s_barrier
	s_add_i32 s58, s58, 2
	s_add_u32 s10, s10, 0x100
	s_addc_u32 s11, s11, 0
	s_cmp_gt_u32 s58, 13
	s_cbranch_scc1 .LBB0_441
.LBB0_439:
	s_branch .LBB0_438
.LBB0_441:
	s_and_b64 vcc, exec, s[42:43]
	s_cbranch_vccz .LBB0_443
	s_barrier
.LBB0_443:
	global_load_dwordx4 v[132:135], v[160:161], off offset:48
	global_load_dwordx4 v[136:139], v[160:161], off offset:32
	global_load_dwordx4 v[140:143], v[160:161], off offset:16
	global_load_dwordx4 v[168:171], v[160:161], off
	global_load_dwordx4 v[194:197], v[162:163], off offset:48
	global_load_dwordx4 v[198:201], v[162:163], off offset:32
	global_load_dwordx4 v[202:205], v[162:163], off offset:16
	global_load_dwordx4 v[214:217], v[162:163], off
	s_waitcnt vmcnt(4)
	v_add_f32_e32 v136, v136, v137
	v_add_f32_e32 v138, v138, v139
	v_mov_b32_e32 v172, v169
	v_mov_b32_e32 v173, v170
	v_mov_b32_e32 v169, v171
	v_mov_b32_e32 v170, v141
	v_mov_b32_e32 v171, v142
	v_mov_b32_e32 v141, v143
	v_pk_add_f32 v[168:169], v[172:173], v[168:169]
	v_pk_add_f32 v[140:141], v[170:171], v[140:141]
	v_pk_add_f32 v[168:169], v[168:169], v[168:169] op_sel:[0,1] op_sel_hi:[1,0]
	v_pk_add_f32 v[140:141], v[140:141], v[140:141] op_sel:[0,1] op_sel_hi:[1,0]
	v_mov_b32_e32 v169, v132
	v_mov_b32_e32 v141, v133
	v_mov_b32_e32 v137, v134
	v_mov_b32_e32 v139, v135
	v_pk_add_f32 v[132:133], v[168:169], v[140:141]
	v_pk_add_f32 v[134:135], v[136:137], v[138:139]
	s_nop 0
	v_pk_add_f32 v[132:133], v[132:133], v[134:135]
	s_nop 0
	v_add_f32_e32 v132, v132, v133
	v_fmamk_f32 v132, v132, 0x3a800000, v209
	v_cmp_gt_f32_e32 vcc, s20, v132
	v_mul_f32_e32 v133, 0x4f800000, v132
	s_nop 0
	v_cndmask_b32_e32 v132, v132, v133, vcc
	v_sqrt_f32_e32 v133, v132
	s_nop 0
	v_add_u32_e32 v134, -1, v133
	v_fma_f32 v135, -v134, v133, v132
	v_cmp_ge_f32_e64 s[0:1], 0, v135
	v_add_u32_e32 v135, 1, v133
	s_nop 0
	v_cndmask_b32_e64 v134, v133, v134, s[0:1]
	v_fma_f32 v133, -v135, v133, v132
	v_cmp_lt_f32_e64 s[0:1], 0, v133
	s_nop 1
	v_cndmask_b32_e64 v133, v134, v135, s[0:1]
	v_mul_f32_e32 v134, 0x37800000, v133
	v_cndmask_b32_e32 v133, v133, v134, vcc
	v_cmp_class_f32_e32 vcc, v132, v210
	s_nop 1
	v_cndmask_b32_e32 v132, v133, v132, vcc
	v_div_scale_f32 v133, s[0:1], v132, v132, 1.0
	v_rcp_f32_e32 v134, v133
	s_nop 0
	v_fma_f32 v135, -v133, v134, 1.0
	v_fmac_f32_e32 v134, v135, v134
	v_div_scale_f32 v135, vcc, 1.0, v132, 1.0
	v_mul_f32_e32 v136, v135, v134
	v_fma_f32 v137, -v133, v136, v135
	v_fmac_f32_e32 v136, v137, v134
	v_fma_f32 v133, -v133, v136, v135
	v_div_fmas_f32 v133, v133, v134, v136
	v_div_fixup_f32 v191, v133, v132, 1.0
	s_waitcnt vmcnt(0)
	v_mov_b64_e32 v[132:133], v[194:195]
	v_mov_b64_e32 v[134:135], v[196:197]
	v_mov_b64_e32 v[136:137], v[198:199]
	v_mov_b64_e32 v[138:139], v[200:201]
	v_mov_b64_e32 v[140:141], v[202:203]
	v_mov_b64_e32 v[142:143], v[204:205]
	v_mov_b64_e32 v[168:169], v[214:215]
	v_mov_b64_e32 v[170:171], v[216:217]
	v_add_f32_e32 v136, v136, v137
	v_add_f32_e32 v138, v138, v139
	v_mov_b32_e32 v172, v169
	v_mov_b32_e32 v173, v170
	v_mov_b32_e32 v169, v171
	v_mov_b32_e32 v170, v141
	v_mov_b32_e32 v171, v142
	v_mov_b32_e32 v141, v143
	v_pk_add_f32 v[168:169], v[172:173], v[168:169]
	v_pk_add_f32 v[140:141], v[170:171], v[140:141]
	v_pk_add_f32 v[168:169], v[168:169], v[168:169] op_sel:[0,1] op_sel_hi:[1,0]
	v_pk_add_f32 v[140:141], v[140:141], v[140:141] op_sel:[0,1] op_sel_hi:[1,0]
	v_mov_b32_e32 v169, v132
	v_mov_b32_e32 v141, v133
	v_mov_b32_e32 v137, v134
	v_mov_b32_e32 v139, v135
	v_pk_add_f32 v[132:133], v[168:169], v[140:141]
	v_pk_add_f32 v[134:135], v[136:137], v[138:139]
	s_nop 0
	v_pk_add_f32 v[132:133], v[132:133], v[134:135]
	s_nop 0
	v_add_f32_e32 v132, v132, v133
	v_fmamk_f32 v132, v132, 0x3a800000, v209
	v_cmp_gt_f32_e32 vcc, s20, v132
	v_mul_f32_e32 v133, 0x4f800000, v132
	s_nop 0
	v_cndmask_b32_e32 v132, v132, v133, vcc
	v_sqrt_f32_e32 v133, v132
	s_nop 0
	v_add_u32_e32 v134, -1, v133
	v_fma_f32 v135, -v134, v133, v132
	v_cmp_ge_f32_e64 s[0:1], 0, v135
	v_add_u32_e32 v135, 1, v133
	s_nop 0
	v_cndmask_b32_e64 v134, v133, v134, s[0:1]
	v_fma_f32 v133, -v135, v133, v132
	v_cmp_lt_f32_e64 s[0:1], 0, v133
	s_nop 1
	v_cndmask_b32_e64 v133, v134, v135, s[0:1]
	v_mul_f32_e32 v134, 0x37800000, v133
	v_cndmask_b32_e32 v133, v133, v134, vcc
	v_cmp_class_f32_e32 vcc, v132, v210
	s_nop 1
	v_cndmask_b32_e32 v132, v133, v132, vcc
	v_div_scale_f32 v133, s[0:1], v132, v132, 1.0
	v_rcp_f32_e32 v134, v133
	s_nop 0
	v_fma_f32 v135, -v133, v134, 1.0
	v_fmac_f32_e32 v134, v135, v134
	v_div_scale_f32 v135, vcc, 1.0, v132, 1.0
	v_mul_f32_e32 v136, v135, v134
	v_fma_f32 v137, -v133, v136, v135
	v_fmac_f32_e32 v136, v137, v134
	v_fma_f32 v133, -v133, v136, v135
	v_div_fmas_f32 v133, v133, v134, v136
	v_div_fixup_f32 v192, v133, v132, 1.0
	v_add_u32_e32 v193, s45, v179
	v_and_or_b32 v132, v211, 64, v178
	s_cmp_gt_i32 s52, 7
	v_lshlrev_b32_e32 v194, 2, v132
	s_mov_b64 s[0:1], -1
	v_or_b32_e32 v200, 16, v193
	v_or_b32_e32 v199, 32, v193
	v_or_b32_e32 v198, 48, v193
	v_add_u32_e32 v197, 0x80, v193
	v_add_u32_e32 v196, 0x90, v193
	v_add_u32_e32 v195, 0xa0, v193
	s_cbranch_scc1 .LBB0_446
	s_andn2_b64 vcc, exec, s[0:1]
	s_cbranch_vccz .LBB0_447

.LBB0_466:
	s_add_u32 s0, s42, s44
	s_addc_u32 s1, s43, s45
	s_add_u32 s0, s0, 0x100
	s_addc_u32 s1, s1, 0
	s_add_u32 s58, s53, s44
	s_addc_u32 s59, s54, s45
	s_add_i32 s60, 0, 0x10000
	s_cmpk_eq_i32 s44, 0x300
	s_cselect_b32 s47, s15, s1
	s_cselect_b32 s46, s18, s0
	v_add_u32_e32 v159, s60, v153
	s_cselect_b32 s1, s19, s59
	s_cselect_b32 s0, s52, s58
	s_add_i32 s61, 0, 0x14000
	ds_read_b128 v[160:163], v159
	ds_read_b128 v[164:167], v159 offset:1024
	ds_read_b128 v[168:171], v159 offset:2048
	ds_read_b128 v[172:175], v159 offset:3072
	v_add_u32_e32 v159, s61, v153
	ds_read_b128 v[176:179], v159
	ds_read_b128 v[188:191], v159 offset:1024
	ds_read_b128 v[192:195], v159 offset:2048
	ds_read_b128 v[196:199], v159 offset:3072
	v_lshl_add_u64 v[180:181], v[148:149], 0, s[44:45]
	s_add_i32 m0, s25, 0xc000
	ds_read_b128 v[200:203], v155
	ds_read_b128 v[204:207], v155 offset:1024
	ds_read_b128 v[214:217], v155 offset:2048
	ds_read_b128 v[218:221], v155 offset:3072
	ds_read_b128 v[222:225], v155 offset:4096
	ds_read_b128 v[226:229], v155 offset:5120
	ds_read_b128 v[230:233], v155 offset:6144
	ds_read_b128 v[234:237], v155 offset:7168
	global_load_lds_dwordx4 v[180:181], off
	v_lshl_add_u64 v[180:181], v[150:151], 0, s[44:45]
	s_add_i32 m0, s25, 0xe000
	s_nop 0
	global_load_lds_dwordx4 v[180:181], off
	s_waitcnt vmcnt(8)
	s_waitcnt lgkmcnt(0)
	s_barrier
	s_setprio 1
	s_waitcnt lgkmcnt(0)
	v_mfma_f32_16x16x32_bf16 v[128:131], v[160:163], v[200:203], v[128:131]
	v_mfma_f32_16x16x32_bf16 v[124:127], v[168:171], v[200:203], v[124:127]
	v_mfma_f32_16x16x32_bf16 v[112:115], v[160:163], v[214:217], v[112:115]
	v_mfma_f32_16x16x32_bf16 v[108:111], v[168:171], v[214:217], v[108:111]
	v_mfma_f32_16x16x32_bf16 v[96:99], v[160:163], v[222:225], v[96:99]
	v_mfma_f32_16x16x32_bf16 v[92:95], v[168:171], v[222:225], v[92:95]
	v_mfma_f32_16x16x32_bf16 v[80:83], v[160:163], v[230:233], v[80:83]
	v_mfma_f32_16x16x32_bf16 v[76:79], v[168:171], v[230:233], v[76:79]
	v_mfma_f32_16x16x32_bf16 v[128:131], v[164:167], v[204:207], v[128:131]
	v_mfma_f32_16x16x32_bf16 v[124:127], v[172:175], v[204:207], v[124:127]
	v_mfma_f32_16x16x32_bf16 v[112:115], v[164:167], v[218:221], v[112:115]
	v_mfma_f32_16x16x32_bf16 v[108:111], v[172:175], v[218:221], v[108:111]
	v_mfma_f32_16x16x32_bf16 v[96:99], v[164:167], v[226:229], v[96:99]
	v_mfma_f32_16x16x32_bf16 v[92:95], v[172:175], v[226:229], v[92:95]
	v_mfma_f32_16x16x32_bf16 v[80:83], v[164:167], v[234:237], v[80:83]
	v_mfma_f32_16x16x32_bf16 v[76:79], v[172:175], v[234:237], v[76:79]
	s_setprio 0
	s_setprio 1
	v_mfma_f32_16x16x32_bf16 v[120:123], v[176:179], v[200:203], v[120:123]
	v_mfma_f32_16x16x32_bf16 v[116:119], v[192:195], v[200:203], v[116:119]
	v_mfma_f32_16x16x32_bf16 v[104:107], v[176:179], v[214:217], v[104:107]
	v_mfma_f32_16x16x32_bf16 v[100:103], v[192:195], v[214:217], v[100:103]
	v_mfma_f32_16x16x32_bf16 v[88:91], v[176:179], v[222:225], v[88:91]
	v_mfma_f32_16x16x32_bf16 v[84:87], v[192:195], v[222:225], v[84:87]
	v_mfma_f32_16x16x32_bf16 v[72:75], v[176:179], v[230:233], v[72:75]
	v_mfma_f32_16x16x32_bf16 v[68:71], v[192:195], v[230:233], v[68:71]
	v_mfma_f32_16x16x32_bf16 v[120:123], v[188:191], v[204:207], v[120:123]
	v_mfma_f32_16x16x32_bf16 v[116:119], v[196:199], v[204:207], v[116:119]
	v_mfma_f32_16x16x32_bf16 v[104:107], v[188:191], v[218:221], v[104:107]
	v_mfma_f32_16x16x32_bf16 v[100:103], v[196:199], v[218:221], v[100:103]
	v_mfma_f32_16x16x32_bf16 v[88:91], v[188:191], v[226:229], v[88:91]
	v_mfma_f32_16x16x32_bf16 v[84:87], v[196:199], v[226:229], v[84:87]
	v_mfma_f32_16x16x32_bf16 v[72:75], v[188:191], v[234:237], v[72:75]
	v_mfma_f32_16x16x32_bf16 v[68:71], v[196:199], v[234:237], v[68:71]
	s_setprio 0
	s_barrier
	s_add_i32 s58, s60, s21
	v_lshl_add_u64 v[180:181], s[0:1], 0, v[136:137]
	s_mov_b32 m0, s58
	ds_read_b128 v[200:203], v155 offset:16384
	ds_read_b128 v[204:207], v155 offset:17408
	ds_read_b128 v[214:217], v155 offset:18432
	ds_read_b128 v[218:221], v155 offset:19456
	ds_read_b128 v[222:225], v155 offset:20480
	ds_read_b128 v[226:229], v155 offset:21504
	ds_read_b128 v[230:233], v155 offset:22528
	ds_read_b128 v[234:237], v155 offset:23552
	global_load_lds_dwordx4 v[180:181], off
	s_add_i32 m0, s58, 0x2000
	s_add_u32 s58, s0, 0x20000
	v_lshl_add_u64 v[182:183], s[0:1], 0, v[132:133]
	s_addc_u32 s59, s1, 0
	s_add_i32 s60, s61, s21
	global_load_lds_dwordx4 v[182:183], off
	v_lshl_add_u64 v[184:185], s[58:59], 0, v[136:137]
	s_mov_b32 m0, s60
	v_lshl_add_u64 v[238:239], s[46:47], 0, v[134:135]
	global_load_lds_dwordx4 v[184:185], off
	v_lshl_add_u64 v[184:185], s[58:59], 0, v[132:133]
	s_add_i32 m0, s60, 0x2000
	s_nop 0
	global_load_lds_dwordx4 v[184:185], off
	v_lshl_add_u64 v[184:185], s[46:47], 0, v[138:139]
	s_mov_b32 m0, s25
	s_nop 0
	global_load_lds_dwordx4 v[184:185], off
	s_mov_b32 m0, s30
	s_nop 0
	global_load_lds_dwordx4 v[238:239], off
	s_waitcnt vmcnt(8)
	s_waitcnt lgkmcnt(0)
	s_barrier
	s_setprio 1
	s_waitcnt lgkmcnt(0)
	v_mfma_f32_16x16x32_bf16 v[64:67], v[160:163], v[200:203], v[64:67]
	v_mfma_f32_16x16x32_bf16 v[60:63], v[168:171], v[200:203], v[60:63]
	v_mfma_f32_16x16x32_bf16 v[48:51], v[160:163], v[214:217], v[48:51]
	v_mfma_f32_16x16x32_bf16 v[44:47], v[168:171], v[214:217], v[44:47]
	v_mfma_f32_16x16x32_bf16 v[32:35], v[160:163], v[222:225], v[32:35]
	v_mfma_f32_16x16x32_bf16 v[28:31], v[168:171], v[222:225], v[28:31]
	v_mfma_f32_16x16x32_bf16 v[16:19], v[160:163], v[230:233], v[16:19]
	v_mfma_f32_16x16x32_bf16 v[12:15], v[168:171], v[230:233], v[12:15]
	v_mfma_f32_16x16x32_bf16 v[64:67], v[164:167], v[204:207], v[64:67]
	v_mfma_f32_16x16x32_bf16 v[60:63], v[172:175], v[204:207], v[60:63]
	v_mfma_f32_16x16x32_bf16 v[48:51], v[164:167], v[218:221], v[48:51]
	v_mfma_f32_16x16x32_bf16 v[44:47], v[172:175], v[218:221], v[44:47]
	v_mfma_f32_16x16x32_bf16 v[32:35], v[164:167], v[226:229], v[32:35]
	v_mfma_f32_16x16x32_bf16 v[28:31], v[172:175], v[226:229], v[28:31]
	v_mfma_f32_16x16x32_bf16 v[16:19], v[164:167], v[234:237], v[16:19]
	v_mfma_f32_16x16x32_bf16 v[12:15], v[172:175], v[234:237], v[12:15]
	s_setprio 0
	s_setprio 1
	v_mfma_f32_16x16x32_bf16 v[56:59], v[176:179], v[200:203], v[56:59]
	v_mfma_f32_16x16x32_bf16 v[52:55], v[192:195], v[200:203], v[52:55]
	v_mfma_f32_16x16x32_bf16 v[40:43], v[176:179], v[214:217], v[40:43]
	v_mfma_f32_16x16x32_bf16 v[36:39], v[192:195], v[214:217], v[36:39]
	v_mfma_f32_16x16x32_bf16 v[24:27], v[176:179], v[222:225], v[24:27]
	v_mfma_f32_16x16x32_bf16 v[20:23], v[192:195], v[222:225], v[20:23]
	v_mfma_f32_16x16x32_bf16 v[8:11], v[176:179], v[230:233], v[8:11]
	v_mfma_f32_16x16x32_bf16 v[4:7], v[192:195], v[230:233], v[4:7]
	v_mfma_f32_16x16x32_bf16 v[56:59], v[188:191], v[204:207], v[56:59]
	v_mfma_f32_16x16x32_bf16 v[52:55], v[196:199], v[204:207], v[52:55]
	v_mfma_f32_16x16x32_bf16 v[40:43], v[188:191], v[218:221], v[40:43]
	v_mfma_f32_16x16x32_bf16 v[36:39], v[196:199], v[218:221], v[36:39]
	v_mfma_f32_16x16x32_bf16 v[24:27], v[188:191], v[226:229], v[24:27]
	v_mfma_f32_16x16x32_bf16 v[20:23], v[196:199], v[226:229], v[20:23]
	v_mfma_f32_16x16x32_bf16 v[8:11], v[188:191], v[234:237], v[8:11]
	v_mfma_f32_16x16x32_bf16 v[4:7], v[196:199], v[234:237], v[4:7]
	s_setprio 0
	s_barrier
	s_add_i32 s58, 0, 0x18000
	v_add_u32_e32 v159, s58, v153
	s_add_i32 s59, 0, 0x1c000
	ds_read_b128 v[160:163], v159
	ds_read_b128 v[164:167], v159 offset:1024
	ds_read_b128 v[168:171], v159 offset:2048
	ds_read_b128 v[172:175], v159 offset:3072
	v_add_u32_e32 v159, s59, v153
	ds_read_b128 v[176:179], v159
	ds_read_b128 v[188:191], v159 offset:1024
	ds_read_b128 v[192:195], v159 offset:2048
	ds_read_b128 v[196:199], v159 offset:3072
	s_add_u32 s46, s46, 0x20000
	s_addc_u32 s47, s47, 0
	s_mov_b32 m0, s31
	v_lshl_add_u64 v[240:241], s[46:47], 0, v[138:139]
	ds_read_b128 v[200:203], v155 offset:32768
	ds_read_b128 v[204:207], v155 offset:33792
	ds_read_b128 v[214:217], v155 offset:34816
	ds_read_b128 v[218:221], v155 offset:35840
	ds_read_b128 v[222:225], v155 offset:36864
	ds_read_b128 v[226:229], v155 offset:37888
	ds_read_b128 v[230:233], v155 offset:38912
	ds_read_b128 v[234:237], v155 offset:39936
	global_load_lds_dwordx4 v[240:241], off
	v_lshl_add_u64 v[240:241], s[46:47], 0, v[134:135]
	s_mov_b32 m0, s33
	s_nop 0
	global_load_lds_dwordx4 v[240:241], off
	s_waitcnt vmcnt(8)
	s_waitcnt lgkmcnt(0)
	s_barrier
	s_setprio 1
	s_waitcnt lgkmcnt(0)
	v_mfma_f32_16x16x32_bf16 v[128:131], v[160:163], v[200:203], v[128:131]
	v_mfma_f32_16x16x32_bf16 v[124:127], v[168:171], v[200:203], v[124:127]
	v_mfma_f32_16x16x32_bf16 v[112:115], v[160:163], v[214:217], v[112:115]
	v_mfma_f32_16x16x32_bf16 v[108:111], v[168:171], v[214:217], v[108:111]
	v_mfma_f32_16x16x32_bf16 v[96:99], v[160:163], v[222:225], v[96:99]
	v_mfma_f32_16x16x32_bf16 v[92:95], v[168:171], v[222:225], v[92:95]
	v_mfma_f32_16x16x32_bf16 v[80:83], v[160:163], v[230:233], v[80:83]
	v_mfma_f32_16x16x32_bf16 v[76:79], v[168:171], v[230:233], v[76:79]
	v_mfma_f32_16x16x32_bf16 v[128:131], v[164:167], v[204:207], v[128:131]
	v_mfma_f32_16x16x32_bf16 v[124:127], v[172:175], v[204:207], v[124:127]
	v_mfma_f32_16x16x32_bf16 v[112:115], v[164:167], v[218:221], v[112:115]
	v_mfma_f32_16x16x32_bf16 v[108:111], v[172:175], v[218:221], v[108:111]
	v_mfma_f32_16x16x32_bf16 v[96:99], v[164:167], v[226:229], v[96:99]
	v_mfma_f32_16x16x32_bf16 v[92:95], v[172:175], v[226:229], v[92:95]
	v_mfma_f32_16x16x32_bf16 v[80:83], v[164:167], v[234:237], v[80:83]
	v_mfma_f32_16x16x32_bf16 v[76:79], v[172:175], v[234:237], v[76:79]
	s_setprio 0
	s_setprio 1
	v_mfma_f32_16x16x32_bf16 v[120:123], v[176:179], v[200:203], v[120:123]
	v_mfma_f32_16x16x32_bf16 v[116:119], v[192:195], v[200:203], v[116:119]
	v_mfma_f32_16x16x32_bf16 v[104:107], v[176:179], v[214:217], v[104:107]
	v_mfma_f32_16x16x32_bf16 v[100:103], v[192:195], v[214:217], v[100:103]
	v_mfma_f32_16x16x32_bf16 v[88:91], v[176:179], v[222:225], v[88:91]
	v_mfma_f32_16x16x32_bf16 v[84:87], v[192:195], v[222:225], v[84:87]
	v_mfma_f32_16x16x32_bf16 v[72:75], v[176:179], v[230:233], v[72:75]
	v_mfma_f32_16x16x32_bf16 v[68:71], v[192:195], v[230:233], v[68:71]
	v_mfma_f32_16x16x32_bf16 v[120:123], v[188:191], v[204:207], v[120:123]
	v_mfma_f32_16x16x32_bf16 v[116:119], v[196:199], v[204:207], v[116:119]
	v_mfma_f32_16x16x32_bf16 v[104:107], v[188:191], v[218:221], v[104:107]
	v_mfma_f32_16x16x32_bf16 v[100:103], v[196:199], v[218:221], v[100:103]
	v_mfma_f32_16x16x32_bf16 v[88:91], v[188:191], v[226:229], v[88:91]
	v_mfma_f32_16x16x32_bf16 v[84:87], v[196:199], v[226:229], v[84:87]
	v_mfma_f32_16x16x32_bf16 v[72:75], v[188:191], v[234:237], v[72:75]
	v_mfma_f32_16x16x32_bf16 v[68:71], v[196:199], v[234:237], v[68:71]
	s_setprio 0
	s_barrier
	s_add_i32 s46, s58, s21
	v_lshl_add_u64 v[180:181], v[180:181], 0, s[34:35]
	s_mov_b32 m0, s46
	ds_read_b128 v[200:203], v155 offset:49152
	ds_read_b128 v[204:207], v155 offset:50176
	ds_read_b128 v[214:217], v155 offset:51200
	ds_read_b128 v[218:221], v155 offset:52224
	ds_read_b128 v[222:225], v155 offset:53248
	ds_read_b128 v[226:229], v155 offset:54272
	ds_read_b128 v[230:233], v155 offset:55296
	ds_read_b128 v[234:237], v155 offset:56320
	global_load_lds_dwordx4 v[180:181], off
	s_add_i32 m0, s46, 0x2000
	s_add_u32 s0, s0, 0x20080
	v_lshl_add_u64 v[180:181], v[182:183], 0, s[34:35]
	s_addc_u32 s1, s1, 0
	s_add_i32 s46, s59, s21
	global_load_lds_dwordx4 v[180:181], off
	v_lshl_add_u64 v[180:181], s[0:1], 0, v[136:137]
	s_mov_b32 m0, s46
	s_nop 0
	global_load_lds_dwordx4 v[180:181], off
	v_lshl_add_u64 v[180:181], s[0:1], 0, v[132:133]
	s_add_i32 m0, s46, 0x2000
	s_nop 0
	global_load_lds_dwordx4 v[180:181], off
	v_lshl_add_u64 v[180:181], v[184:185], 0, s[34:35]
	s_mov_b32 m0, s48
	s_nop 0
	global_load_lds_dwordx4 v[180:181], off
	v_lshl_add_u64 v[180:181], v[238:239], 0, s[34:35]
	s_mov_b32 m0, s49
	s_nop 0
	global_load_lds_dwordx4 v[180:181], off
	s_waitcnt vmcnt(8)
	s_waitcnt lgkmcnt(0)
	s_barrier
	s_setprio 1
	s_waitcnt lgkmcnt(0)
	v_mfma_f32_16x16x32_bf16 v[64:67], v[160:163], v[200:203], v[64:67]
	v_mfma_f32_16x16x32_bf16 v[60:63], v[168:171], v[200:203], v[60:63]
	v_mfma_f32_16x16x32_bf16 v[48:51], v[160:163], v[214:217], v[48:51]
	v_mfma_f32_16x16x32_bf16 v[44:47], v[168:171], v[214:217], v[44:47]
	v_mfma_f32_16x16x32_bf16 v[32:35], v[160:163], v[222:225], v[32:35]
	v_mfma_f32_16x16x32_bf16 v[28:31], v[168:171], v[222:225], v[28:31]
	v_mfma_f32_16x16x32_bf16 v[16:19], v[160:163], v[230:233], v[16:19]
	v_mfma_f32_16x16x32_bf16 v[12:15], v[168:171], v[230:233], v[12:15]
	v_mfma_f32_16x16x32_bf16 v[64:67], v[164:167], v[204:207], v[64:67]
	v_mfma_f32_16x16x32_bf16 v[60:63], v[172:175], v[204:207], v[60:63]
	v_mfma_f32_16x16x32_bf16 v[48:51], v[164:167], v[218:221], v[48:51]
	v_mfma_f32_16x16x32_bf16 v[44:47], v[172:175], v[218:221], v[44:47]
	v_mfma_f32_16x16x32_bf16 v[32:35], v[164:167], v[226:229], v[32:35]
	v_mfma_f32_16x16x32_bf16 v[28:31], v[172:175], v[226:229], v[28:31]
	v_mfma_f32_16x16x32_bf16 v[16:19], v[164:167], v[234:237], v[16:19]
	v_mfma_f32_16x16x32_bf16 v[12:15], v[172:175], v[234:237], v[12:15]
	s_setprio 0
	s_setprio 1
	v_mfma_f32_16x16x32_bf16 v[56:59], v[176:179], v[200:203], v[56:59]
	v_mfma_f32_16x16x32_bf16 v[52:55], v[192:195], v[200:203], v[52:55]
	v_mfma_f32_16x16x32_bf16 v[40:43], v[176:179], v[214:217], v[40:43]
	v_mfma_f32_16x16x32_bf16 v[36:39], v[192:195], v[214:217], v[36:39]
	v_mfma_f32_16x16x32_bf16 v[24:27], v[176:179], v[222:225], v[24:27]
	v_mfma_f32_16x16x32_bf16 v[20:23], v[192:195], v[222:225], v[20:23]
	v_mfma_f32_16x16x32_bf16 v[8:11], v[176:179], v[230:233], v[8:11]
	v_mfma_f32_16x16x32_bf16 v[4:7], v[192:195], v[230:233], v[4:7]
	v_mfma_f32_16x16x32_bf16 v[56:59], v[188:191], v[204:207], v[56:59]
	v_mfma_f32_16x16x32_bf16 v[52:55], v[196:199], v[204:207], v[52:55]
	v_mfma_f32_16x16x32_bf16 v[40:43], v[188:191], v[218:221], v[40:43]
	v_mfma_f32_16x16x32_bf16 v[36:39], v[196:199], v[218:221], v[36:39]
	v_mfma_f32_16x16x32_bf16 v[24:27], v[188:191], v[226:229], v[24:27]
	v_mfma_f32_16x16x32_bf16 v[20:23], v[196:199], v[226:229], v[20:23]
	v_mfma_f32_16x16x32_bf16 v[8:11], v[188:191], v[234:237], v[8:11]
	v_mfma_f32_16x16x32_bf16 v[4:7], v[196:199], v[234:237], v[4:7]
	s_setprio 0
	s_barrier
	s_add_i32 s55, s55, 2
	s_add_u32 s44, s44, 0x100
	s_addc_u32 s45, s45, 0
	s_cmp_gt_u32 s55, 5
	s_cbranch_scc1 .LBB0_469
.LBB0_467:
	s_branch .LBB0_466
.LBB0_469:
	s_and_b64 vcc, exec, s[10:11]
	s_cbranch_vccz .LBB0_471
	s_barrier
.LBB0_471:
	global_load_dwordx4 v[158:161], v[144:145], off
	global_load_dwordx4 v[162:165], v[144:145], off offset:16
	global_load_dwordx4 v[188:191], v[146:147], off
	global_load_dwordx4 v[192:195], v[146:147], off offset:16
	s_waitcnt vmcnt(2)
	v_mov_b32_e32 v166, v158
	v_mov_b32_e32 v167, v162
	v_mov_b32_e32 v162, v159
	v_pk_add_f32 v[158:159], v[166:167], v[162:163]
	v_mov_b32_e32 v162, v160
	v_mov_b32_e32 v163, v164
	v_mov_b32_e32 v164, v161
	v_pk_add_f32 v[160:161], v[162:163], v[164:165]
	s_nop 0
	v_pk_add_f32 v[158:159], v[158:159], v[160:161]
	s_nop 0
	v_add_f32_e32 v157, v158, v159
	v_fmamk_f32 v157, v157, 0x3b000000, v209
	v_cmp_gt_f32_e32 vcc, s20, v157
	v_mul_f32_e32 v158, 0x4f800000, v157
	s_nop 0
	v_cndmask_b32_e32 v157, v157, v158, vcc
	v_sqrt_f32_e32 v158, v157
	s_nop 0
	v_add_u32_e32 v159, -1, v158
	v_fma_f32 v160, -v159, v158, v157
	v_cmp_ge_f32_e64 s[0:1], 0, v160
	v_add_u32_e32 v160, 1, v158
	s_nop 0
	v_cndmask_b32_e64 v159, v158, v159, s[0:1]
	v_fma_f32 v158, -v160, v158, v157
	v_cmp_lt_f32_e64 s[0:1], 0, v158
	s_nop 1
	v_cndmask_b32_e64 v158, v159, v160, s[0:1]
	v_mul_f32_e32 v159, 0x37800000, v158
	v_cndmask_b32_e32 v158, v158, v159, vcc
	v_cmp_class_f32_e32 vcc, v157, v210
	s_nop 1
	v_cndmask_b32_e32 v157, v158, v157, vcc
	v_div_scale_f32 v158, s[0:1], v157, v157, 1.0
	v_rcp_f32_e32 v159, v158
	s_nop 0
	v_fma_f32 v160, -v158, v159, 1.0
	v_fmac_f32_e32 v159, v160, v159
	v_div_scale_f32 v160, vcc, 1.0, v157, 1.0
	v_mul_f32_e32 v161, v160, v159
	v_fma_f32 v162, -v158, v161, v160
	v_fmac_f32_e32 v161, v162, v159
	v_fma_f32 v158, -v158, v161, v160
	v_div_fmas_f32 v158, v158, v159, v161
	v_div_fixup_f32 v157, v158, v157, 1.0
	s_waitcnt vmcnt(0)
	v_mov_b64_e32 v[158:159], v[188:189]
	v_mov_b64_e32 v[160:161], v[190:191]
	v_mov_b64_e32 v[162:163], v[192:193]
	v_mov_b64_e32 v[164:165], v[194:195]
	s_waitcnt vmcnt(1)
	v_mov_b32_e32 v166, v158
	s_waitcnt vmcnt(0)
	v_mov_b32_e32 v167, v162
	v_mov_b32_e32 v162, v159
	v_pk_add_f32 v[158:159], v[166:167], v[162:163]
	v_mov_b32_e32 v162, v160
	v_mov_b32_e32 v163, v164
	v_mov_b32_e32 v164, v161
	v_pk_add_f32 v[160:161], v[162:163], v[164:165]
	s_nop 0
	v_pk_add_f32 v[158:159], v[158:159], v[160:161]
	s_nop 0
	v_add_f32_e32 v158, v158, v159
	v_fmamk_f32 v158, v158, 0x3b000000, v209
	v_cmp_gt_f32_e32 vcc, s20, v158
	v_mul_f32_e32 v159, 0x4f800000, v158
	s_nop 0
	v_cndmask_b32_e32 v158, v158, v159, vcc
	v_sqrt_f32_e32 v159, v158
	s_nop 0
	v_add_u32_e32 v160, -1, v159
	v_fma_f32 v161, -v160, v159, v158
	v_cmp_ge_f32_e64 s[0:1], 0, v161
	v_add_u32_e32 v161, 1, v159
	s_nop 0
	v_cndmask_b32_e64 v160, v159, v160, s[0:1]
	v_fma_f32 v159, -v161, v159, v158
	v_cmp_lt_f32_e64 s[0:1], 0, v159
	s_nop 1
	v_cndmask_b32_e64 v159, v160, v161, s[0:1]
	v_mul_f32_e32 v160, 0x37800000, v159
	v_cndmask_b32_e32 v159, v159, v160, vcc
	v_cmp_class_f32_e32 vcc, v158, v210
	s_nop 1
	v_cndmask_b32_e32 v158, v159, v158, vcc
	v_div_scale_f32 v159, s[0:1], v158, v158, 1.0
	v_rcp_f32_e32 v160, v159
	s_nop 0
	v_fma_f32 v161, -v159, v160, 1.0
	v_fmac_f32_e32 v160, v161, v160
	v_div_scale_f32 v161, vcc, 1.0, v158, 1.0
	v_mul_f32_e32 v162, v161, v160
	v_fma_f32 v163, -v159, v162, v161
	v_fmac_f32_e32 v162, v163, v160
	v_fma_f32 v159, -v159, v162, v161
	v_div_fmas_f32 v159, v159, v160, v162
	v_div_fixup_f32 v158, v159, v158, 1.0
	s_cmp_lt_i32 s51, 8
	s_mov_b32 s0, 0x49400000
	s_cselect_b32 s0, s0, 0x4d600000
	s_add_u32 s0, s38, s0
	v_add_u32_e32 v146, s13, v152
	s_addc_u32 s1, s39, 0
	s_lshl_b32 s13, s51, 9
	ds_bpermute_b32 v148, v156, v157
	s_and_b32 s13, s13, 0xe00
	s_add_u32 s0, s0, s13
	s_addc_u32 s1, s1, 0
	v_ashrrev_i32_e32 v147, 31, v146
	v_lshl_add_u64 v[150:151], s[0:1], 0, v[2:3]
	v_lshlrev_b64 v[144:145], 12, v[146:147]
	v_lshl_add_u64 v[144:145], v[150:151], 0, v[144:145]
	s_waitcnt lgkmcnt(0)
	v_pk_mul_f32 v[130:131], v[130:131], v[148:149] op_sel_hi:[1,0]
	v_pk_mul_f32 v[128:129], v[128:129], v[148:149] op_sel_hi:[1,0]
	v_pk_mul_f32 v[160:161], v[126:127], v[148:149] op_sel_hi:[1,0]
	v_pk_mul_f32 v[126:127], v[124:125], v[148:149] op_sel_hi:[1,0]
	v_cvt_pk_bf16_f32 v124, v128, v129
	v_cvt_pk_bf16_f32 v125, v130, v131
	v_pk_mul_f32 v[120:121], v[120:121], v[148:149] op_sel_hi:[1,0]
	v_cvt_pk_bf16_f32 v126, v126, v127
	v_cvt_pk_bf16_f32 v127, v160, v161
	global_store_dwordx4 v[144:145], v[124:127], off
	v_pk_mul_f32 v[122:123], v[122:123], v[148:149] op_sel_hi:[1,0]
	s_mov_b32 s0, 0x80000
	v_pk_mul_f32 v[124:125], v[118:119], v[148:149] op_sel_hi:[1,0]
	v_pk_mul_f32 v[118:119], v[116:117], v[148:149] op_sel_hi:[1,0]
	v_cvt_pk_bf16_f32 v116, v120, v121
	v_cvt_pk_bf16_f32 v117, v122, v123
	s_nop 0
	v_cvt_pk_bf16_f32 v118, v118, v119
	v_cvt_pk_bf16_f32 v119, v124, v125
	global_store_dwordx4 v[144:145], v[116:119], off offset:256
	ds_bpermute_b32 v116, v156, v158
	s_waitcnt lgkmcnt(0)
	v_pk_mul_f32 v[114:115], v[114:115], v[116:117] op_sel_hi:[1,0]
	v_or_b32_e32 v118, 16, v146
	v_ashrrev_i32_e32 v119, 31, v118
	v_lshlrev_b64 v[118:119], 12, v[118:119]
	v_lshl_add_u64 v[118:119], v[150:151], 0, v[118:119]
	v_pk_mul_f32 v[112:113], v[112:113], v[116:117] op_sel_hi:[1,0]
	v_pk_mul_f32 v[120:121], v[110:111], v[116:117] op_sel_hi:[1,0]
	v_pk_mul_f32 v[110:111], v[108:109], v[116:117] op_sel_hi:[1,0]
	v_cvt_pk_bf16_f32 v108, v112, v113
	v_cvt_pk_bf16_f32 v109, v114, v115
	v_pk_mul_f32 v[104:105], v[104:105], v[116:117] op_sel_hi:[1,0]
	v_cvt_pk_bf16_f32 v110, v110, v111
	v_cvt_pk_bf16_f32 v111, v120, v121
	global_store_dwordx4 v[118:119], v[108:111], off
	v_pk_mul_f32 v[106:107], v[106:107], v[116:117] op_sel_hi:[1,0]
	s_nop 0
	v_pk_mul_f32 v[108:109], v[102:103], v[116:117] op_sel_hi:[1,0]
	v_pk_mul_f32 v[102:103], v[100:101], v[116:117] op_sel_hi:[1,0]
	v_cvt_pk_bf16_f32 v100, v104, v105
	v_cvt_pk_bf16_f32 v101, v106, v107
	s_nop 0
	v_cvt_pk_bf16_f32 v102, v102, v103
	v_cvt_pk_bf16_f32 v103, v108, v109
	global_store_dwordx4 v[118:119], v[100:103], off offset:256
	ds_bpermute_b32 v100, v156, v157 offset:64
	s_waitcnt lgkmcnt(0)
	v_pk_mul_f32 v[98:99], v[98:99], v[100:101] op_sel_hi:[1,0]
	v_or_b32_e32 v102, 32, v146
	v_ashrrev_i32_e32 v103, 31, v102
	v_lshlrev_b64 v[102:103], 12, v[102:103]
	v_lshl_add_u64 v[102:103], v[150:151], 0, v[102:103]
	v_pk_mul_f32 v[96:97], v[96:97], v[100:101] op_sel_hi:[1,0]
	v_pk_mul_f32 v[104:105], v[94:95], v[100:101] op_sel_hi:[1,0]
	v_pk_mul_f32 v[94:95], v[92:93], v[100:101] op_sel_hi:[1,0]
	v_cvt_pk_bf16_f32 v92, v96, v97
	v_cvt_pk_bf16_f32 v93, v98, v99
	v_pk_mul_f32 v[88:89], v[88:89], v[100:101] op_sel_hi:[1,0]
	v_cvt_pk_bf16_f32 v94, v94, v95
	v_cvt_pk_bf16_f32 v95, v104, v105
	global_store_dwordx4 v[102:103], v[92:95], off
	v_pk_mul_f32 v[90:91], v[90:91], v[100:101] op_sel_hi:[1,0]
	s_nop 0
	v_pk_mul_f32 v[92:93], v[86:87], v[100:101] op_sel_hi:[1,0]
	v_pk_mul_f32 v[86:87], v[84:85], v[100:101] op_sel_hi:[1,0]
	v_cvt_pk_bf16_f32 v84, v88, v89
	v_cvt_pk_bf16_f32 v85, v90, v91
	s_nop 0
	v_cvt_pk_bf16_f32 v86, v86, v87
	v_cvt_pk_bf16_f32 v87, v92, v93
	global_store_dwordx4 v[102:103], v[84:87], off offset:256
	ds_bpermute_b32 v84, v156, v158 offset:64
	s_waitcnt lgkmcnt(0)
	v_pk_mul_f32 v[82:83], v[82:83], v[84:85] op_sel_hi:[1,0]
	v_or_b32_e32 v86, 48, v146
	v_ashrrev_i32_e32 v87, 31, v86
	v_lshlrev_b64 v[86:87], 12, v[86:87]
	v_lshl_add_u64 v[86:87], v[150:151], 0, v[86:87]
	v_pk_mul_f32 v[80:81], v[80:81], v[84:85] op_sel_hi:[1,0]
	v_pk_mul_f32 v[88:89], v[78:79], v[84:85] op_sel_hi:[1,0]
	v_pk_mul_f32 v[78:79], v[76:77], v[84:85] op_sel_hi:[1,0]
	v_cvt_pk_bf16_f32 v76, v80, v81
	v_cvt_pk_bf16_f32 v77, v82, v83
	v_pk_mul_f32 v[72:73], v[72:73], v[84:85] op_sel_hi:[1,0]
	v_cvt_pk_bf16_f32 v78, v78, v79
	v_cvt_pk_bf16_f32 v79, v88, v89
	global_store_dwordx4 v[86:87], v[76:79], off
	v_pk_mul_f32 v[74:75], v[74:75], v[84:85] op_sel_hi:[1,0]
	s_nop 0
	v_pk_mul_f32 v[76:77], v[70:71], v[84:85] op_sel_hi:[1,0]
	v_pk_mul_f32 v[70:71], v[68:69], v[84:85] op_sel_hi:[1,0]
	v_cvt_pk_bf16_f32 v68, v72, v73
	ds_bpermute_b32 v72, v156, v157 offset:128
	v_cvt_pk_bf16_f32 v69, v74, v75
	v_cvt_pk_bf16_f32 v70, v70, v71
	v_cvt_pk_bf16_f32 v71, v76, v77
	global_store_dwordx4 v[86:87], v[68:71], off offset:256
	s_waitcnt lgkmcnt(0)
	v_pk_mul_f32 v[64:65], v[64:65], v[72:73] op_sel_hi:[1,0]
	v_pk_mul_f32 v[66:67], v[66:67], v[72:73] op_sel_hi:[1,0]
	v_pk_mul_f32 v[70:71], v[62:63], v[72:73] op_sel_hi:[1,0]
	v_pk_mul_f32 v[62:63], v[60:61], v[72:73] op_sel_hi:[1,0]
	v_cvt_pk_bf16_f32 v60, v64, v65
	v_add_co_u32_e32 v64, vcc, s0, v144
	v_cvt_pk_bf16_f32 v61, v66, v67
	v_pk_mul_f32 v[56:57], v[56:57], v[72:73] op_sel_hi:[1,0]
	s_nop 0
	v_addc_co_u32_e32 v65, vcc, 0, v145, vcc
	v_cvt_pk_bf16_f32 v62, v62, v63
	v_cvt_pk_bf16_f32 v63, v70, v71
	global_store_dwordx4 v[64:65], v[60:63], off
	v_lshl_add_u64 v[68:69], v[144:145], 0, s[84:85]
	v_pk_mul_f32 v[58:59], v[58:59], v[72:73] op_sel_hi:[1,0]
	v_pk_mul_f32 v[60:61], v[54:55], v[72:73] op_sel_hi:[1,0]
	v_pk_mul_f32 v[54:55], v[52:53], v[72:73] op_sel_hi:[1,0]
	v_cvt_pk_bf16_f32 v52, v56, v57
	ds_bpermute_b32 v56, v156, v158 offset:128
	v_cvt_pk_bf16_f32 v53, v58, v59
	s_mov_b64 s[0:1], 0x90000
	v_cvt_pk_bf16_f32 v54, v54, v55
	v_cvt_pk_bf16_f32 v55, v60, v61
	global_store_dwordx4 v[68:69], v[52:55], off offset:256
	s_waitcnt lgkmcnt(0)
	v_pk_mul_f32 v[48:49], v[48:49], v[56:57] op_sel_hi:[1,0]
	v_pk_mul_f32 v[50:51], v[50:51], v[56:57] op_sel_hi:[1,0]
	v_lshl_add_u64 v[52:53], v[144:145], 0, s[0:1]
	s_mov_b32 s0, 0x90000
	v_pk_mul_f32 v[54:55], v[46:47], v[56:57] op_sel_hi:[1,0]
	v_pk_mul_f32 v[46:47], v[44:45], v[56:57] op_sel_hi:[1,0]
	v_cvt_pk_bf16_f32 v44, v48, v49
	v_add_co_u32_e32 v48, vcc, s0, v144
	v_cvt_pk_bf16_f32 v45, v50, v51
	v_pk_mul_f32 v[40:41], v[40:41], v[56:57] op_sel_hi:[1,0]
	s_nop 0
	v_addc_co_u32_e32 v49, vcc, 0, v145, vcc
	v_cvt_pk_bf16_f32 v46, v46, v47
	v_cvt_pk_bf16_f32 v47, v54, v55
	global_store_dwordx4 v[48:49], v[44:47], off
	v_pk_mul_f32 v[42:43], v[42:43], v[56:57] op_sel_hi:[1,0]
	s_mov_b64 s[0:1], 0xa0000
	v_pk_mul_f32 v[44:45], v[38:39], v[56:57] op_sel_hi:[1,0]
	v_pk_mul_f32 v[38:39], v[36:37], v[56:57] op_sel_hi:[1,0]
	v_cvt_pk_bf16_f32 v36, v40, v41
	ds_bpermute_b32 v40, v156, v157 offset:192
	v_cvt_pk_bf16_f32 v37, v42, v43
	v_cvt_pk_bf16_f32 v38, v38, v39
	v_cvt_pk_bf16_f32 v39, v44, v45
	global_store_dwordx4 v[52:53], v[36:39], off offset:256
	s_waitcnt lgkmcnt(0)
	v_pk_mul_f32 v[32:33], v[32:33], v[40:41] op_sel_hi:[1,0]
	v_pk_mul_f32 v[34:35], v[34:35], v[40:41] op_sel_hi:[1,0]
	v_lshl_add_u64 v[36:37], v[144:145], 0, s[0:1]
	s_mov_b32 s0, 0xa0000
	v_pk_mul_f32 v[38:39], v[30:31], v[40:41] op_sel_hi:[1,0]
	v_pk_mul_f32 v[30:31], v[28:29], v[40:41] op_sel_hi:[1,0]
	v_cvt_pk_bf16_f32 v28, v32, v33
	v_add_co_u32_e32 v32, vcc, s0, v144
	v_cvt_pk_bf16_f32 v29, v34, v35
	v_pk_mul_f32 v[24:25], v[24:25], v[40:41] op_sel_hi:[1,0]
	s_nop 0
	v_addc_co_u32_e32 v33, vcc, 0, v145, vcc
	v_cvt_pk_bf16_f32 v30, v30, v31
	v_cvt_pk_bf16_f32 v31, v38, v39
	global_store_dwordx4 v[32:33], v[28:31], off
	v_pk_mul_f32 v[26:27], v[26:27], v[40:41] op_sel_hi:[1,0]
	s_mov_b64 s[0:1], 0xb0000
	v_pk_mul_f32 v[28:29], v[22:23], v[40:41] op_sel_hi:[1,0]
	v_pk_mul_f32 v[22:23], v[20:21], v[40:41] op_sel_hi:[1,0]
	v_cvt_pk_bf16_f32 v20, v24, v25
	ds_bpermute_b32 v24, v156, v158 offset:192
	v_cvt_pk_bf16_f32 v21, v26, v27
	v_cvt_pk_bf16_f32 v22, v22, v23
	v_cvt_pk_bf16_f32 v23, v28, v29
	global_store_dwordx4 v[36:37], v[20:23], off offset:256
	s_waitcnt lgkmcnt(0)
	v_pk_mul_f32 v[16:17], v[16:17], v[24:25] op_sel_hi:[1,0]
	v_pk_mul_f32 v[18:19], v[18:19], v[24:25] op_sel_hi:[1,0]
	v_lshl_add_u64 v[20:21], v[144:145], 0, s[0:1]
	s_mov_b32 s0, 0xb0000
	v_pk_mul_f32 v[22:23], v[14:15], v[24:25] op_sel_hi:[1,0]
	v_pk_mul_f32 v[14:15], v[12:13], v[24:25] op_sel_hi:[1,0]
	v_cvt_pk_bf16_f32 v12, v16, v17
	v_add_co_u32_e32 v16, vcc, s0, v144
	v_cvt_pk_bf16_f32 v13, v18, v19
	v_cvt_pk_bf16_f32 v14, v14, v15
	v_cvt_pk_bf16_f32 v15, v22, v23
	s_mov_b64 s[0:1], -1
	s_nop 0
	v_addc_co_u32_e32 v17, vcc, 0, v145, vcc
	global_store_dwordx4 v[16:17], v[12:15], off
	s_andn2_b64 vcc, exec, s[16:17]
	v_pk_mul_f32 v[10:11], v[10:11], v[24:25] op_sel_hi:[1,0]
	v_pk_mul_f32 v[12:13], v[6:7], v[24:25] op_sel_hi:[1,0]
	v_pk_mul_f32 v[6:7], v[4:5], v[24:25] op_sel_hi:[1,0]
	v_pk_mul_f32 v[8:9], v[8:9], v[24:25] op_sel_hi:[1,0]
	s_nop 0
	v_cvt_pk_bf16_f32 v4, v8, v9
	v_cvt_pk_bf16_f32 v5, v10, v11
	v_cvt_pk_bf16_f32 v6, v6, v7
	v_cvt_pk_bf16_f32 v7, v12, v13
	global_store_dwordx4 v[20:21], v[4:7], off offset:256
	s_cbranch_vccnz .LBB0_456
	s_andn2_b64 vcc, exec, s[4:5]
	s_cbranch_vccnz .LBB0_455
	s_barrier
	s_branch .LBB0_455
